# out-proj epilogue out_pre stores (dwordx4) marked sc1 write-through so the L2 holds less dirty data at the following grid barrier
# baseline (speedup 1.0000x reference)
.LBB0_650:
	s_or_b64 exec, exec, s[68:69]
	v_lshl_add_u32 v210, s90, 8, v223
	v_lshl_or_b32 v2, s66, 8, v225
	s_mov_b64 s[6:7], -1
	s_cmpk_lt_i32 s90, 0x100
	v_ashrrev_i32_e32 v211, 31, v210
	v_ashrrev_i32_e32 v3, 31, v2
	s_cbranch_scc1 .LBB0_668
	v_add_u32_e32 v132, 0xffff0000, v210
	v_ashrrev_i32_e32 v133, 31, v132
	v_readlane_b32 s68, v254, 16
	v_readlane_b32 s36, v254, 50
	v_ashrrev_i32_e32 v1, 5, v132
	v_lshlrev_b64 v[132:133], 12, v[132:133]
	v_readlane_b32 s70, v254, 18
	v_readlane_b32 s71, v254, 19
	v_readlane_b32 s37, v254, 51
	v_add_u32_e32 v1, 32, v1
	v_lshl_add_u64 v[134:135], s[70:71], 0, v[132:133]
	v_mov_b64_e32 v[132:133], s[36:37]
	v_mad_i64_i32 v[132:133], s[6:7], v1, s99, v[132:133]
	v_lshl_add_u64 v[152:153], v[132:133], 0, s[54:55]
	v_lshlrev_b64 v[132:133], 2, v[2:3]
	v_lshl_add_u64 v[154:155], v[134:135], 0, v[132:133]
	v_lshl_add_u64 v[134:135], v[152:153], 0, v[132:133]
	global_load_dwordx4 v[136:139], v[134:135], off
	global_load_dwordx4 v[140:143], v[154:155], off
	global_load_dwordx4 v[144:147], v[154:155], off offset:16
	global_load_dwordx4 v[148:151], v[134:135], off offset:16
	v_lshlrev_b64 v[156:157], 11, v[210:211]
	v_or_b32_e32 v134, 0x80, v2
	v_lshl_add_u64 v[156:157], s[40:41], 0, v[156:157]
	v_ashrrev_i32_e32 v135, 31, v134
	v_lshl_add_u64 v[156:157], v[2:3], 1, v[156:157]
	v_lshl_add_u64 v[152:153], v[134:135], 2, v[152:153]
	v_readlane_b32 s69, v254, 17
	v_readlane_b32 s72, v254, 20
	v_readlane_b32 s73, v254, 21
	v_readlane_b32 s74, v254, 22
	v_readlane_b32 s75, v254, 23
	v_readlane_b32 s76, v254, 24
	v_readlane_b32 s77, v254, 25
	v_readlane_b32 s78, v254, 26
	v_readlane_b32 s79, v254, 27
	v_readlane_b32 s80, v254, 28
	v_readlane_b32 s81, v254, 29
	v_readlane_b32 s82, v254, 30
	v_readlane_b32 s83, v254, 31
	v_readlane_b32 s38, v254, 52
	v_readlane_b32 s39, v254, 53
	s_waitcnt vmcnt(0)
	v_pk_fma_f32 v[158:159], v[6:7], v[138:139], v[142:143]
	v_pk_fma_f32 v[160:161], v[4:5], v[136:137], v[140:141]
	v_pk_fma_f32 v[162:163], v[10:11], v[150:151], v[146:147]
	v_pk_fma_f32 v[164:165], v[8:9], v[148:149], v[144:145]
	v_cvt_pk_bf16_f32 v136, v160, v161
	v_cvt_pk_bf16_f32 v137, v158, v159
	v_cvt_pk_bf16_f32 v138, v164, v165
	v_cvt_pk_bf16_f32 v139, v162, v163
	global_store_dwordx4 v[156:157], v[136:139], off sc1
	global_load_dwordx4 v[136:139], v[152:153], off
	s_nop 0
	global_load_dwordx4 v[140:143], v[154:155], off offset:512
	global_load_dwordx4 v[144:147], v[154:155], off offset:528
	global_load_dwordx4 v[148:151], v[152:153], off offset:16
	v_mul_f32_e32 v1, v161, v161
	v_mul_f32_e32 v152, v159, v159
	v_mul_f32_e32 v153, v165, v165
	v_fmac_f32_e32 v1, v160, v160
	v_fmac_f32_e32 v152, v158, v158
	v_mul_f32_e32 v154, v163, v163
	v_fmac_f32_e32 v153, v164, v164
	v_add_f32_e32 v1, v1, v152
	v_fmac_f32_e32 v154, v162, v162
	v_add_f32_e32 v1, v1, v153
	v_add_f32_e32 v1, v154, v1
	s_waitcnt vmcnt(0)
	v_pk_fma_f32 v[142:143], v[38:39], v[138:139], v[142:143]
	v_pk_fma_f32 v[136:137], v[36:37], v[136:137], v[140:141]
	v_pk_fma_f32 v[140:141], v[40:41], v[148:149], v[144:145]
	v_mul_f32_e32 v138, v137, v137
	v_mul_f32_e32 v139, v143, v143
	v_pk_fma_f32 v[146:147], v[42:43], v[150:151], v[146:147]
	v_mul_f32_e32 v144, v141, v141
	v_fmac_f32_e32 v138, v136, v136
	v_fmac_f32_e32 v139, v142, v142
	v_mul_f32_e32 v145, v147, v147
	v_fmac_f32_e32 v144, v140, v140
	v_add_f32_e32 v138, v138, v139
	v_add_f32_e32 v138, v138, v144
	v_fmac_f32_e32 v145, v146, v146
	v_add_f32_e32 v138, v145, v138
	v_add_f32_e32 v1, v1, v138
	ds_bpermute_b32 v139, v226, v1
	v_cvt_pk_bf16_f32 v138, v136, v137
	v_cvt_pk_bf16_f32 v140, v140, v141
	v_cvt_pk_bf16_f32 v141, v146, v147
	s_waitcnt lgkmcnt(0)
	v_add_f32_e32 v1, v1, v139
	ds_bpermute_b32 v136, v227, v1
	v_cvt_pk_bf16_f32 v139, v142, v143
	global_store_dwordx4 v[156:157], v[138:141], off offset:256 sc1
	s_and_saveexec_b64 s[6:7], s[8:9]
	s_cbranch_execz .LBB0_653
	s_waitcnt lgkmcnt(0)
	v_add_f32_e32 v1, v1, v136
	s_lshl_b32 s34, s66, 2
	v_lshlrev_b64 v[136:137], 6, v[210:211]
	s_ashr_i32 s35, s34, 31
	v_lshl_add_u64 v[136:137], s[18:19], 0, v[136:137]
	v_lshl_add_u64 v[136:137], s[34:35], 2, v[136:137]
	s_lshl_b32 s14, s42, 2
	v_lshl_add_u64 v[136:137], v[136:137], 0, s[14:15]
	global_store_dword v[136:137], v1, off
.LBB0_653:
	s_or_b64 exec, exec, s[6:7]
	s_waitcnt lgkmcnt(0)
	v_add_u32_e32 v136, 0xffff0010, v210
	v_readlane_b32 s36, v254, 50
	v_ashrrev_i32_e32 v1, 5, v136
	v_readlane_b32 s37, v254, 51
	v_add_u32_e32 v1, 32, v1
	v_ashrrev_i32_e32 v137, 31, v136
	v_readlane_b32 s68, v254, 16
	v_mov_b64_e32 v[138:139], s[36:37]
	v_lshlrev_b64 v[136:137], 12, v[136:137]
	v_readlane_b32 s70, v254, 18
	v_readlane_b32 s71, v254, 19
	v_mad_i64_i32 v[138:139], s[6:7], v1, s99, v[138:139]
	s_nop 0
	v_lshl_add_u64 v[136:137], s[70:71], 0, v[136:137]
	v_lshl_add_u64 v[154:155], v[138:139], 0, s[54:55]
	v_lshl_add_u64 v[156:157], v[136:137], 0, v[132:133]
	v_lshl_add_u64 v[136:137], v[154:155], 0, v[132:133]
	global_load_dwordx4 v[138:141], v[136:137], off
	global_load_dwordx4 v[142:145], v[156:157], off
	global_load_dwordx4 v[146:149], v[156:157], off offset:16
	global_load_dwordx4 v[150:153], v[136:137], off offset:16
	v_or_b32_e32 v136, 16, v210
	v_ashrrev_i32_e32 v137, 31, v136
	v_lshlrev_b64 v[158:159], 11, v[136:137]
	v_lshl_add_u64 v[158:159], s[40:41], 0, v[158:159]
	v_lshl_add_u64 v[158:159], v[2:3], 1, v[158:159]
	v_lshl_add_u64 v[154:155], v[134:135], 2, v[154:155]
	v_readlane_b32 s69, v254, 17
	v_readlane_b32 s72, v254, 20
	v_readlane_b32 s73, v254, 21
	v_readlane_b32 s74, v254, 22
	v_readlane_b32 s75, v254, 23
	v_readlane_b32 s76, v254, 24
	v_readlane_b32 s77, v254, 25
	v_readlane_b32 s78, v254, 26
	v_readlane_b32 s79, v254, 27
	v_readlane_b32 s80, v254, 28
	v_readlane_b32 s81, v254, 29
	v_readlane_b32 s82, v254, 30
	v_readlane_b32 s83, v254, 31
	v_readlane_b32 s38, v254, 52
	v_readlane_b32 s39, v254, 53
	s_waitcnt vmcnt(2)
	v_pk_fma_f32 v[160:161], v[14:15], v[140:141], v[144:145]
	v_pk_fma_f32 v[162:163], v[12:13], v[138:139], v[142:143]
	s_waitcnt vmcnt(0)
	v_pk_fma_f32 v[164:165], v[18:19], v[152:153], v[148:149]
	v_pk_fma_f32 v[166:167], v[16:17], v[150:151], v[146:147]
	v_cvt_pk_bf16_f32 v138, v162, v163
	v_cvt_pk_bf16_f32 v139, v160, v161
	v_cvt_pk_bf16_f32 v140, v166, v167
	v_cvt_pk_bf16_f32 v141, v164, v165
	global_store_dwordx4 v[158:159], v[138:141], off sc1
	global_load_dwordx4 v[138:141], v[154:155], off
	s_nop 0
	global_load_dwordx4 v[142:145], v[156:157], off offset:512
	global_load_dwordx4 v[146:149], v[156:157], off offset:528
	global_load_dwordx4 v[150:153], v[154:155], off offset:16
	v_mul_f32_e32 v1, v163, v163
	v_mul_f32_e32 v154, v161, v161
	v_mul_f32_e32 v155, v167, v167
	v_fmac_f32_e32 v1, v162, v162
	v_fmac_f32_e32 v154, v160, v160
	v_mul_f32_e32 v156, v165, v165
	v_fmac_f32_e32 v155, v166, v166
	v_add_f32_e32 v1, v1, v154
	v_fmac_f32_e32 v156, v164, v164
	v_add_f32_e32 v1, v1, v155
	v_add_f32_e32 v1, v156, v1
	s_waitcnt vmcnt(2)
	v_pk_fma_f32 v[144:145], v[46:47], v[140:141], v[144:145]
	v_pk_fma_f32 v[138:139], v[44:45], v[138:139], v[142:143]
	s_waitcnt vmcnt(0)
	v_pk_fma_f32 v[142:143], v[48:49], v[150:151], v[146:147]
	v_mul_f32_e32 v140, v139, v139
	v_mul_f32_e32 v141, v145, v145
	v_pk_fma_f32 v[148:149], v[50:51], v[152:153], v[148:149]
	v_mul_f32_e32 v146, v143, v143
	v_fmac_f32_e32 v140, v138, v138
	v_fmac_f32_e32 v141, v144, v144
	v_mul_f32_e32 v147, v149, v149
	v_fmac_f32_e32 v146, v142, v142
	v_add_f32_e32 v140, v140, v141
	v_add_f32_e32 v140, v140, v146
	v_fmac_f32_e32 v147, v148, v148
	v_add_f32_e32 v140, v147, v140
	v_add_f32_e32 v1, v1, v140
	ds_bpermute_b32 v141, v226, v1
	v_cvt_pk_bf16_f32 v140, v138, v139
	v_cvt_pk_bf16_f32 v142, v142, v143
	v_cvt_pk_bf16_f32 v143, v148, v149
	s_waitcnt lgkmcnt(0)
	v_add_f32_e32 v1, v1, v141
	ds_bpermute_b32 v138, v227, v1
	v_cvt_pk_bf16_f32 v141, v144, v145
	global_store_dwordx4 v[158:159], v[140:143], off offset:256 sc1
	s_and_saveexec_b64 s[6:7], s[8:9]
	s_cbranch_execz .LBB0_655
	s_lshl_b32 s34, s66, 2
	v_lshlrev_b64 v[136:137], 6, v[136:137]
	s_ashr_i32 s35, s34, 31
	v_lshl_add_u64 v[136:137], s[18:19], 0, v[136:137]
	v_lshl_add_u64 v[136:137], s[34:35], 2, v[136:137]
	s_lshl_b32 s14, s42, 2
	s_waitcnt lgkmcnt(0)
	v_add_f32_e32 v1, v1, v138
	v_lshl_add_u64 v[136:137], v[136:137], 0, s[14:15]
	global_store_dword v[136:137], v1, off
.LBB0_655:
	s_or_b64 exec, exec, s[6:7]
	v_add_u32_e32 v136, 0xffff0020, v210
	v_readlane_b32 s36, v254, 50
	v_ashrrev_i32_e32 v1, 5, v136
	v_readlane_b32 s37, v254, 51
	v_add_u32_e32 v1, 32, v1
	v_ashrrev_i32_e32 v137, 31, v136
	v_readlane_b32 s68, v254, 16
	s_waitcnt lgkmcnt(0)
	v_mov_b64_e32 v[138:139], s[36:37]
	v_lshlrev_b64 v[136:137], 12, v[136:137]
	v_readlane_b32 s70, v254, 18
	v_readlane_b32 s71, v254, 19
	v_mad_i64_i32 v[138:139], s[6:7], v1, s99, v[138:139]
	s_nop 0
	v_lshl_add_u64 v[136:137], s[70:71], 0, v[136:137]
	v_lshl_add_u64 v[154:155], v[138:139], 0, s[54:55]
	v_lshl_add_u64 v[156:157], v[136:137], 0, v[132:133]
	v_lshl_add_u64 v[136:137], v[154:155], 0, v[132:133]
	global_load_dwordx4 v[138:141], v[136:137], off
	global_load_dwordx4 v[142:145], v[156:157], off
	global_load_dwordx4 v[146:149], v[156:157], off offset:16
	global_load_dwordx4 v[150:153], v[136:137], off offset:16
	v_or_b32_e32 v136, 32, v210
	v_ashrrev_i32_e32 v137, 31, v136
	v_lshlrev_b64 v[158:159], 11, v[136:137]
	v_lshl_add_u64 v[158:159], s[40:41], 0, v[158:159]
	v_lshl_add_u64 v[158:159], v[2:3], 1, v[158:159]
	v_lshl_add_u64 v[154:155], v[134:135], 2, v[154:155]
	v_readlane_b32 s69, v254, 17
	v_readlane_b32 s72, v254, 20
	v_readlane_b32 s73, v254, 21
	v_readlane_b32 s74, v254, 22
	v_readlane_b32 s75, v254, 23
	v_readlane_b32 s76, v254, 24
	v_readlane_b32 s77, v254, 25
	v_readlane_b32 s78, v254, 26
	v_readlane_b32 s79, v254, 27
	v_readlane_b32 s80, v254, 28
	v_readlane_b32 s81, v254, 29
	v_readlane_b32 s82, v254, 30
	v_readlane_b32 s83, v254, 31
	v_readlane_b32 s38, v254, 52
	v_readlane_b32 s39, v254, 53
	s_waitcnt vmcnt(2)
	v_pk_fma_f32 v[160:161], v[22:23], v[140:141], v[144:145]
	v_pk_fma_f32 v[162:163], v[20:21], v[138:139], v[142:143]
	s_waitcnt vmcnt(0)
	v_pk_fma_f32 v[164:165], v[26:27], v[152:153], v[148:149]
	v_pk_fma_f32 v[166:167], v[24:25], v[150:151], v[146:147]
	v_cvt_pk_bf16_f32 v138, v162, v163
	v_cvt_pk_bf16_f32 v139, v160, v161
	v_cvt_pk_bf16_f32 v140, v166, v167
	v_cvt_pk_bf16_f32 v141, v164, v165
	global_store_dwordx4 v[158:159], v[138:141], off sc1
	global_load_dwordx4 v[138:141], v[154:155], off
	s_nop 0
	global_load_dwordx4 v[142:145], v[156:157], off offset:512
	global_load_dwordx4 v[146:149], v[156:157], off offset:528
	global_load_dwordx4 v[150:153], v[154:155], off offset:16
	v_mul_f32_e32 v1, v163, v163
	v_mul_f32_e32 v154, v161, v161
	v_mul_f32_e32 v155, v167, v167
	v_fmac_f32_e32 v1, v162, v162
	v_fmac_f32_e32 v154, v160, v160
	v_mul_f32_e32 v156, v165, v165
	v_fmac_f32_e32 v155, v166, v166
	v_add_f32_e32 v1, v1, v154
	v_fmac_f32_e32 v156, v164, v164
	v_add_f32_e32 v1, v1, v155
	v_add_f32_e32 v1, v156, v1
	s_waitcnt vmcnt(2)
	v_pk_fma_f32 v[144:145], v[54:55], v[140:141], v[144:145]
	v_pk_fma_f32 v[138:139], v[52:53], v[138:139], v[142:143]
	s_waitcnt vmcnt(0)
	v_pk_fma_f32 v[142:143], v[56:57], v[150:151], v[146:147]
	v_mul_f32_e32 v140, v139, v139
	v_mul_f32_e32 v141, v145, v145
	v_pk_fma_f32 v[148:149], v[58:59], v[152:153], v[148:149]
	v_mul_f32_e32 v146, v143, v143
	v_fmac_f32_e32 v140, v138, v138
	v_fmac_f32_e32 v141, v144, v144
	v_mul_f32_e32 v147, v149, v149
	v_fmac_f32_e32 v146, v142, v142
	v_add_f32_e32 v140, v140, v141
	v_add_f32_e32 v140, v140, v146
	v_fmac_f32_e32 v147, v148, v148
	v_add_f32_e32 v140, v147, v140
	v_add_f32_e32 v1, v1, v140
	ds_bpermute_b32 v141, v226, v1
	v_cvt_pk_bf16_f32 v140, v138, v139
	v_cvt_pk_bf16_f32 v142, v142, v143
	v_cvt_pk_bf16_f32 v143, v148, v149
	s_waitcnt lgkmcnt(0)
	v_add_f32_e32 v1, v1, v141
	ds_bpermute_b32 v138, v227, v1
	v_cvt_pk_bf16_f32 v141, v144, v145
	global_store_dwordx4 v[158:159], v[140:143], off offset:256 sc1
	s_and_saveexec_b64 s[6:7], s[8:9]
	s_cbranch_execz .LBB0_657
	s_lshl_b32 s34, s66, 2
	v_lshlrev_b64 v[136:137], 6, v[136:137]
	s_ashr_i32 s35, s34, 31
	v_lshl_add_u64 v[136:137], s[18:19], 0, v[136:137]
	v_lshl_add_u64 v[136:137], s[34:35], 2, v[136:137]
	s_lshl_b32 s14, s42, 2
	s_waitcnt lgkmcnt(0)
	v_add_f32_e32 v1, v1, v138
	v_lshl_add_u64 v[136:137], v[136:137], 0, s[14:15]
	global_store_dword v[136:137], v1, off
.LBB0_657:
	s_or_b64 exec, exec, s[6:7]
	v_add_u32_e32 v136, 0xffff0030, v210
	v_readlane_b32 s36, v254, 50
	v_ashrrev_i32_e32 v1, 5, v136
	v_readlane_b32 s37, v254, 51
	v_add_u32_e32 v1, 32, v1
	v_ashrrev_i32_e32 v137, 31, v136
	v_readlane_b32 s68, v254, 16
	s_waitcnt lgkmcnt(0)
	v_mov_b64_e32 v[138:139], s[36:37]
	v_lshlrev_b64 v[136:137], 12, v[136:137]
	v_readlane_b32 s70, v254, 18
	v_readlane_b32 s71, v254, 19
	v_mad_i64_i32 v[138:139], s[6:7], v1, s99, v[138:139]
	s_nop 0
	v_lshl_add_u64 v[136:137], s[70:71], 0, v[136:137]
	v_lshl_add_u64 v[154:155], v[138:139], 0, s[54:55]
	v_lshl_add_u64 v[156:157], v[136:137], 0, v[132:133]
	v_lshl_add_u64 v[136:137], v[154:155], 0, v[132:133]
	global_load_dwordx4 v[138:141], v[136:137], off
	global_load_dwordx4 v[142:145], v[156:157], off
	global_load_dwordx4 v[146:149], v[156:157], off offset:16
	global_load_dwordx4 v[150:153], v[136:137], off offset:16
	v_or_b32_e32 v136, 48, v210
	v_ashrrev_i32_e32 v137, 31, v136
	v_lshlrev_b64 v[158:159], 11, v[136:137]
	v_lshl_add_u64 v[158:159], s[40:41], 0, v[158:159]
	v_lshl_add_u64 v[158:159], v[2:3], 1, v[158:159]
	v_lshl_add_u64 v[154:155], v[134:135], 2, v[154:155]
	v_readlane_b32 s69, v254, 17
	v_readlane_b32 s72, v254, 20
	v_readlane_b32 s73, v254, 21
	v_readlane_b32 s74, v254, 22
	v_readlane_b32 s75, v254, 23
	v_readlane_b32 s76, v254, 24
	v_readlane_b32 s77, v254, 25
	v_readlane_b32 s78, v254, 26
	v_readlane_b32 s79, v254, 27
	v_readlane_b32 s80, v254, 28
	v_readlane_b32 s81, v254, 29
	v_readlane_b32 s82, v254, 30
	v_readlane_b32 s83, v254, 31
	v_readlane_b32 s38, v254, 52
	v_readlane_b32 s39, v254, 53
	s_waitcnt vmcnt(2)
	v_pk_fma_f32 v[160:161], v[30:31], v[140:141], v[144:145]
	v_pk_fma_f32 v[162:163], v[28:29], v[138:139], v[142:143]
	s_waitcnt vmcnt(0)
	v_pk_fma_f32 v[164:165], v[34:35], v[152:153], v[148:149]
	v_pk_fma_f32 v[166:167], v[32:33], v[150:151], v[146:147]
	v_cvt_pk_bf16_f32 v138, v162, v163
	v_cvt_pk_bf16_f32 v139, v160, v161
	v_cvt_pk_bf16_f32 v140, v166, v167
	v_cvt_pk_bf16_f32 v141, v164, v165
	global_store_dwordx4 v[158:159], v[138:141], off sc1
	global_load_dwordx4 v[138:141], v[154:155], off
	s_nop 0
	global_load_dwordx4 v[142:145], v[156:157], off offset:512
	global_load_dwordx4 v[146:149], v[156:157], off offset:528
	global_load_dwordx4 v[150:153], v[154:155], off offset:16
	v_mul_f32_e32 v1, v163, v163
	v_mul_f32_e32 v154, v161, v161
	v_mul_f32_e32 v155, v167, v167
	v_fmac_f32_e32 v1, v162, v162
	v_fmac_f32_e32 v154, v160, v160
	v_mul_f32_e32 v156, v165, v165
	v_fmac_f32_e32 v155, v166, v166
	v_add_f32_e32 v1, v1, v154
	v_fmac_f32_e32 v156, v164, v164
	v_add_f32_e32 v1, v1, v155
	v_add_f32_e32 v1, v156, v1
	s_waitcnt vmcnt(2)
	v_pk_fma_f32 v[144:145], v[62:63], v[140:141], v[144:145]
	v_pk_fma_f32 v[138:139], v[60:61], v[138:139], v[142:143]
	s_waitcnt vmcnt(0)
	v_pk_fma_f32 v[142:143], v[64:65], v[150:151], v[146:147]
	v_mul_f32_e32 v140, v139, v139
	v_mul_f32_e32 v141, v145, v145
	v_pk_fma_f32 v[148:149], v[66:67], v[152:153], v[148:149]
	v_mul_f32_e32 v146, v143, v143
	v_fmac_f32_e32 v140, v138, v138
	v_fmac_f32_e32 v141, v144, v144
	v_mul_f32_e32 v147, v149, v149
	v_fmac_f32_e32 v146, v142, v142
	v_add_f32_e32 v140, v140, v141
	v_add_f32_e32 v140, v140, v146
	v_fmac_f32_e32 v147, v148, v148
	v_add_f32_e32 v140, v147, v140
	v_add_f32_e32 v1, v1, v140
	ds_bpermute_b32 v141, v226, v1
	v_cvt_pk_bf16_f32 v140, v138, v139
	v_cvt_pk_bf16_f32 v142, v142, v143
	v_cvt_pk_bf16_f32 v143, v148, v149
	s_waitcnt lgkmcnt(0)
	v_add_f32_e32 v1, v1, v141
	ds_bpermute_b32 v138, v227, v1
	v_cvt_pk_bf16_f32 v141, v144, v145
	global_store_dwordx4 v[158:159], v[140:143], off offset:256 sc1
	s_and_saveexec_b64 s[6:7], s[8:9]
	s_cbranch_execz .LBB0_659
	s_lshl_b32 s34, s66, 2
	v_lshlrev_b64 v[136:137], 6, v[136:137]
	s_ashr_i32 s35, s34, 31
	v_lshl_add_u64 v[136:137], s[18:19], 0, v[136:137]
	v_lshl_add_u64 v[136:137], s[34:35], 2, v[136:137]
	s_lshl_b32 s14, s42, 2
	s_waitcnt lgkmcnt(0)
	v_add_f32_e32 v1, v1, v138
	v_lshl_add_u64 v[136:137], v[136:137], 0, s[14:15]
	global_store_dword v[136:137], v1, off
.LBB0_659:
	s_or_b64 exec, exec, s[6:7]
	v_add_u32_e32 v136, 0xffff0080, v210
	v_readlane_b32 s36, v254, 50
	v_ashrrev_i32_e32 v1, 5, v136
	v_readlane_b32 s37, v254, 51
	v_add_u32_e32 v1, 32, v1
	v_ashrrev_i32_e32 v137, 31, v136
	v_readlane_b32 s68, v254, 16
	s_waitcnt lgkmcnt(0)
	v_mov_b64_e32 v[138:139], s[36:37]
	v_lshlrev_b64 v[136:137], 12, v[136:137]
	v_readlane_b32 s70, v254, 18
	v_readlane_b32 s71, v254, 19
	v_mad_i64_i32 v[138:139], s[6:7], v1, s99, v[138:139]
	s_nop 0
	v_lshl_add_u64 v[136:137], s[70:71], 0, v[136:137]
	v_lshl_add_u64 v[154:155], v[138:139], 0, s[54:55]
	v_lshl_add_u64 v[156:157], v[136:137], 0, v[132:133]
	v_lshl_add_u64 v[136:137], v[154:155], 0, v[132:133]
	global_load_dwordx4 v[138:141], v[136:137], off
	global_load_dwordx4 v[142:145], v[156:157], off
	global_load_dwordx4 v[146:149], v[156:157], off offset:16
	global_load_dwordx4 v[150:153], v[136:137], off offset:16
	v_add_u32_e32 v136, 0x80, v210
	v_ashrrev_i32_e32 v137, 31, v136
	v_lshlrev_b64 v[158:159], 11, v[136:137]
	v_lshl_add_u64 v[158:159], s[40:41], 0, v[158:159]
	v_lshl_add_u64 v[158:159], v[2:3], 1, v[158:159]
	v_lshl_add_u64 v[154:155], v[134:135], 2, v[154:155]
	v_readlane_b32 s69, v254, 17
	v_readlane_b32 s72, v254, 20
	v_readlane_b32 s73, v254, 21
	v_readlane_b32 s74, v254, 22
	v_readlane_b32 s75, v254, 23
	v_readlane_b32 s76, v254, 24
	v_readlane_b32 s77, v254, 25
	v_readlane_b32 s78, v254, 26
	v_readlane_b32 s79, v254, 27
	v_readlane_b32 s80, v254, 28
	v_readlane_b32 s81, v254, 29
	v_readlane_b32 s82, v254, 30
	v_readlane_b32 s83, v254, 31
	v_readlane_b32 s38, v254, 52
	v_readlane_b32 s39, v254, 53
	s_waitcnt vmcnt(2)
	v_pk_fma_f32 v[160:161], v[70:71], v[140:141], v[144:145]
	v_pk_fma_f32 v[162:163], v[68:69], v[138:139], v[142:143]
	s_waitcnt vmcnt(0)
	v_pk_fma_f32 v[164:165], v[74:75], v[152:153], v[148:149]
	v_pk_fma_f32 v[166:167], v[72:73], v[150:151], v[146:147]
	v_cvt_pk_bf16_f32 v138, v162, v163
	v_cvt_pk_bf16_f32 v139, v160, v161
	v_cvt_pk_bf16_f32 v140, v166, v167
	v_cvt_pk_bf16_f32 v141, v164, v165
	global_store_dwordx4 v[158:159], v[138:141], off sc1
	global_load_dwordx4 v[138:141], v[154:155], off
	s_nop 0
	global_load_dwordx4 v[142:145], v[156:157], off offset:512
	global_load_dwordx4 v[146:149], v[156:157], off offset:528
	global_load_dwordx4 v[150:153], v[154:155], off offset:16
	v_mul_f32_e32 v1, v163, v163
	v_mul_f32_e32 v154, v161, v161
	v_mul_f32_e32 v155, v167, v167
	v_fmac_f32_e32 v1, v162, v162
	v_fmac_f32_e32 v154, v160, v160
	v_mul_f32_e32 v156, v165, v165
	v_fmac_f32_e32 v155, v166, v166
	v_add_f32_e32 v1, v1, v154
	v_fmac_f32_e32 v156, v164, v164
	v_add_f32_e32 v1, v1, v155
	v_add_f32_e32 v1, v156, v1
	s_waitcnt vmcnt(2)
	v_pk_fma_f32 v[144:145], v[102:103], v[140:141], v[144:145]
	v_pk_fma_f32 v[138:139], v[100:101], v[138:139], v[142:143]
	s_waitcnt vmcnt(0)
	v_pk_fma_f32 v[142:143], v[104:105], v[150:151], v[146:147]
	v_mul_f32_e32 v140, v139, v139
	v_mul_f32_e32 v141, v145, v145
	v_pk_fma_f32 v[148:149], v[106:107], v[152:153], v[148:149]
	v_mul_f32_e32 v146, v143, v143
	v_fmac_f32_e32 v140, v138, v138
	v_fmac_f32_e32 v141, v144, v144
	v_mul_f32_e32 v147, v149, v149
	v_fmac_f32_e32 v146, v142, v142
	v_add_f32_e32 v140, v140, v141
	v_add_f32_e32 v140, v140, v146
	v_fmac_f32_e32 v147, v148, v148
	v_add_f32_e32 v140, v147, v140
	v_add_f32_e32 v1, v1, v140
	ds_bpermute_b32 v141, v226, v1
	v_cvt_pk_bf16_f32 v140, v138, v139
	v_cvt_pk_bf16_f32 v142, v142, v143
	v_cvt_pk_bf16_f32 v143, v148, v149
	s_waitcnt lgkmcnt(0)
	v_add_f32_e32 v1, v1, v141
	ds_bpermute_b32 v138, v227, v1
	v_cvt_pk_bf16_f32 v141, v144, v145
	global_store_dwordx4 v[158:159], v[140:143], off offset:256 sc1
	s_and_saveexec_b64 s[6:7], s[8:9]
	s_cbranch_execz .LBB0_661
	s_lshl_b32 s34, s66, 2
	v_lshlrev_b64 v[136:137], 6, v[136:137]
	s_ashr_i32 s35, s34, 31
	v_lshl_add_u64 v[136:137], s[18:19], 0, v[136:137]
	v_lshl_add_u64 v[136:137], s[34:35], 2, v[136:137]
	s_lshl_b32 s14, s42, 2
	s_waitcnt lgkmcnt(0)
	v_add_f32_e32 v1, v1, v138
	v_lshl_add_u64 v[136:137], v[136:137], 0, s[14:15]
	global_store_dword v[136:137], v1, off
.LBB0_661:
	s_or_b64 exec, exec, s[6:7]
	v_add_u32_e32 v136, 0xffff0090, v210
	v_readlane_b32 s36, v254, 50
	v_ashrrev_i32_e32 v1, 5, v136
	v_readlane_b32 s37, v254, 51
	v_add_u32_e32 v1, 32, v1
	v_ashrrev_i32_e32 v137, 31, v136
	v_readlane_b32 s68, v254, 16
	s_waitcnt lgkmcnt(0)
	v_mov_b64_e32 v[138:139], s[36:37]
	v_lshlrev_b64 v[136:137], 12, v[136:137]
	v_readlane_b32 s70, v254, 18
	v_readlane_b32 s71, v254, 19
	v_mad_i64_i32 v[138:139], s[6:7], v1, s99, v[138:139]
	s_nop 0
	v_lshl_add_u64 v[136:137], s[70:71], 0, v[136:137]
	v_lshl_add_u64 v[154:155], v[138:139], 0, s[54:55]
	v_lshl_add_u64 v[156:157], v[136:137], 0, v[132:133]
	v_lshl_add_u64 v[136:137], v[154:155], 0, v[132:133]
	global_load_dwordx4 v[138:141], v[136:137], off
	global_load_dwordx4 v[142:145], v[156:157], off
	global_load_dwordx4 v[146:149], v[156:157], off offset:16
	global_load_dwordx4 v[150:153], v[136:137], off offset:16
	v_add_u32_e32 v136, 0x90, v210
	v_ashrrev_i32_e32 v137, 31, v136
	v_lshlrev_b64 v[158:159], 11, v[136:137]
	v_lshl_add_u64 v[158:159], s[40:41], 0, v[158:159]
	v_lshl_add_u64 v[158:159], v[2:3], 1, v[158:159]
	v_lshl_add_u64 v[154:155], v[134:135], 2, v[154:155]
	v_readlane_b32 s69, v254, 17
	v_readlane_b32 s72, v254, 20
	v_readlane_b32 s73, v254, 21
	v_readlane_b32 s74, v254, 22
	v_readlane_b32 s75, v254, 23
	v_readlane_b32 s76, v254, 24
	v_readlane_b32 s77, v254, 25
	v_readlane_b32 s78, v254, 26
	v_readlane_b32 s79, v254, 27
	v_readlane_b32 s80, v254, 28
	v_readlane_b32 s81, v254, 29
	v_readlane_b32 s82, v254, 30
	v_readlane_b32 s83, v254, 31
	v_readlane_b32 s38, v254, 52
	v_readlane_b32 s39, v254, 53
	s_waitcnt vmcnt(2)
	v_pk_fma_f32 v[160:161], v[78:79], v[140:141], v[144:145]
	v_pk_fma_f32 v[162:163], v[76:77], v[138:139], v[142:143]
	s_waitcnt vmcnt(0)
	v_pk_fma_f32 v[164:165], v[82:83], v[152:153], v[148:149]
	v_pk_fma_f32 v[166:167], v[80:81], v[150:151], v[146:147]
	v_cvt_pk_bf16_f32 v138, v162, v163
	v_cvt_pk_bf16_f32 v139, v160, v161
	v_cvt_pk_bf16_f32 v140, v166, v167
	v_cvt_pk_bf16_f32 v141, v164, v165
	global_store_dwordx4 v[158:159], v[138:141], off sc1
	global_load_dwordx4 v[138:141], v[154:155], off
	s_nop 0
	global_load_dwordx4 v[142:145], v[156:157], off offset:512
	global_load_dwordx4 v[146:149], v[156:157], off offset:528
	global_load_dwordx4 v[150:153], v[154:155], off offset:16
	v_mul_f32_e32 v1, v163, v163
	v_mul_f32_e32 v154, v161, v161
	v_mul_f32_e32 v155, v167, v167
	v_fmac_f32_e32 v1, v162, v162
	v_fmac_f32_e32 v154, v160, v160
	v_mul_f32_e32 v156, v165, v165
	v_fmac_f32_e32 v155, v166, v166
	v_add_f32_e32 v1, v1, v154
	v_fmac_f32_e32 v156, v164, v164
	v_add_f32_e32 v1, v1, v155
	v_add_f32_e32 v1, v156, v1
	s_waitcnt vmcnt(2)
	v_pk_fma_f32 v[144:145], v[110:111], v[140:141], v[144:145]
	v_pk_fma_f32 v[138:139], v[108:109], v[138:139], v[142:143]
	s_waitcnt vmcnt(0)
	v_pk_fma_f32 v[142:143], v[112:113], v[150:151], v[146:147]
	v_mul_f32_e32 v140, v139, v139
	v_mul_f32_e32 v141, v145, v145
	v_pk_fma_f32 v[148:149], v[114:115], v[152:153], v[148:149]
	v_mul_f32_e32 v146, v143, v143
	v_fmac_f32_e32 v140, v138, v138
	v_fmac_f32_e32 v141, v144, v144
	v_mul_f32_e32 v147, v149, v149
	v_fmac_f32_e32 v146, v142, v142
	v_add_f32_e32 v140, v140, v141
	v_add_f32_e32 v140, v140, v146
	v_fmac_f32_e32 v147, v148, v148
	v_add_f32_e32 v140, v147, v140
	v_add_f32_e32 v1, v1, v140
	ds_bpermute_b32 v141, v226, v1
	v_cvt_pk_bf16_f32 v140, v138, v139
	v_cvt_pk_bf16_f32 v142, v142, v143
	v_cvt_pk_bf16_f32 v143, v148, v149
	s_waitcnt lgkmcnt(0)
	v_add_f32_e32 v1, v1, v141
	ds_bpermute_b32 v138, v227, v1
	v_cvt_pk_bf16_f32 v141, v144, v145
	global_store_dwordx4 v[158:159], v[140:143], off offset:256 sc1
	s_and_saveexec_b64 s[6:7], s[8:9]
	s_cbranch_execz .LBB0_663
	s_lshl_b32 s34, s66, 2
	v_lshlrev_b64 v[136:137], 6, v[136:137]
	s_ashr_i32 s35, s34, 31
	v_lshl_add_u64 v[136:137], s[18:19], 0, v[136:137]
	v_lshl_add_u64 v[136:137], s[34:35], 2, v[136:137]
	s_lshl_b32 s14, s42, 2
	s_waitcnt lgkmcnt(0)
	v_add_f32_e32 v1, v1, v138
	v_lshl_add_u64 v[136:137], v[136:137], 0, s[14:15]
	global_store_dword v[136:137], v1, off
.LBB0_663:
	s_or_b64 exec, exec, s[6:7]
	v_add_u32_e32 v136, 0xffff00a0, v210
	v_readlane_b32 s36, v254, 50
	v_ashrrev_i32_e32 v1, 5, v136
	v_readlane_b32 s37, v254, 51
	v_add_u32_e32 v1, 32, v1
	v_ashrrev_i32_e32 v137, 31, v136
	v_readlane_b32 s68, v254, 16
	s_waitcnt lgkmcnt(0)
	v_mov_b64_e32 v[138:139], s[36:37]
	v_lshlrev_b64 v[136:137], 12, v[136:137]
	v_readlane_b32 s70, v254, 18
	v_readlane_b32 s71, v254, 19
	v_mad_i64_i32 v[138:139], s[6:7], v1, s99, v[138:139]
	s_nop 0
	v_lshl_add_u64 v[136:137], s[70:71], 0, v[136:137]
	v_lshl_add_u64 v[154:155], v[138:139], 0, s[54:55]
	v_lshl_add_u64 v[156:157], v[136:137], 0, v[132:133]
	v_lshl_add_u64 v[136:137], v[154:155], 0, v[132:133]
	global_load_dwordx4 v[138:141], v[136:137], off
	global_load_dwordx4 v[142:145], v[156:157], off
	global_load_dwordx4 v[146:149], v[156:157], off offset:16
	global_load_dwordx4 v[150:153], v[136:137], off offset:16
	v_add_u32_e32 v136, 0xa0, v210
	v_ashrrev_i32_e32 v137, 31, v136
	v_lshlrev_b64 v[158:159], 11, v[136:137]
	v_lshl_add_u64 v[158:159], s[40:41], 0, v[158:159]
	v_lshl_add_u64 v[158:159], v[2:3], 1, v[158:159]
	v_lshl_add_u64 v[154:155], v[134:135], 2, v[154:155]
	v_readlane_b32 s69, v254, 17
	v_readlane_b32 s72, v254, 20
	v_readlane_b32 s73, v254, 21
	v_readlane_b32 s74, v254, 22
	v_readlane_b32 s75, v254, 23
	v_readlane_b32 s76, v254, 24
	v_readlane_b32 s77, v254, 25
	v_readlane_b32 s78, v254, 26
	v_readlane_b32 s79, v254, 27
	v_readlane_b32 s80, v254, 28
	v_readlane_b32 s81, v254, 29
	v_readlane_b32 s82, v254, 30
	v_readlane_b32 s83, v254, 31
	v_readlane_b32 s38, v254, 52
	v_readlane_b32 s39, v254, 53
	s_waitcnt vmcnt(2)
	v_pk_fma_f32 v[160:161], v[86:87], v[140:141], v[144:145]
	v_pk_fma_f32 v[162:163], v[84:85], v[138:139], v[142:143]
	s_waitcnt vmcnt(0)
	v_pk_fma_f32 v[164:165], v[90:91], v[152:153], v[148:149]
	v_pk_fma_f32 v[166:167], v[88:89], v[150:151], v[146:147]
	v_cvt_pk_bf16_f32 v138, v162, v163
	v_cvt_pk_bf16_f32 v139, v160, v161
	v_cvt_pk_bf16_f32 v140, v166, v167
	v_cvt_pk_bf16_f32 v141, v164, v165
	global_store_dwordx4 v[158:159], v[138:141], off sc1
	global_load_dwordx4 v[138:141], v[154:155], off
	s_nop 0
	global_load_dwordx4 v[142:145], v[156:157], off offset:512
	global_load_dwordx4 v[146:149], v[156:157], off offset:528
	global_load_dwordx4 v[150:153], v[154:155], off offset:16
	v_mul_f32_e32 v1, v163, v163
	v_mul_f32_e32 v154, v161, v161
	v_mul_f32_e32 v155, v167, v167
	v_fmac_f32_e32 v1, v162, v162
	v_fmac_f32_e32 v154, v160, v160
	v_mul_f32_e32 v156, v165, v165
	v_fmac_f32_e32 v155, v166, v166
	v_add_f32_e32 v1, v1, v154
	v_fmac_f32_e32 v156, v164, v164
	v_add_f32_e32 v1, v1, v155
	v_add_f32_e32 v1, v156, v1
	s_waitcnt vmcnt(2)
	v_pk_fma_f32 v[144:145], v[118:119], v[140:141], v[144:145]
	v_pk_fma_f32 v[138:139], v[116:117], v[138:139], v[142:143]
	s_waitcnt vmcnt(0)
	v_pk_fma_f32 v[142:143], v[120:121], v[150:151], v[146:147]
	v_mul_f32_e32 v140, v139, v139
	v_mul_f32_e32 v141, v145, v145
	v_pk_fma_f32 v[148:149], v[122:123], v[152:153], v[148:149]
	v_mul_f32_e32 v146, v143, v143
	v_fmac_f32_e32 v140, v138, v138
	v_fmac_f32_e32 v141, v144, v144
	v_mul_f32_e32 v147, v149, v149
	v_fmac_f32_e32 v146, v142, v142
	v_add_f32_e32 v140, v140, v141
	v_add_f32_e32 v140, v140, v146
	v_fmac_f32_e32 v147, v148, v148
	v_add_f32_e32 v140, v147, v140
	v_add_f32_e32 v1, v1, v140
	ds_bpermute_b32 v141, v226, v1
	v_cvt_pk_bf16_f32 v140, v138, v139
	v_cvt_pk_bf16_f32 v142, v142, v143
	v_cvt_pk_bf16_f32 v143, v148, v149
	s_waitcnt lgkmcnt(0)
	v_add_f32_e32 v1, v1, v141
	ds_bpermute_b32 v138, v227, v1
	v_cvt_pk_bf16_f32 v141, v144, v145
	global_store_dwordx4 v[158:159], v[140:143], off offset:256 sc1
	s_and_saveexec_b64 s[6:7], s[8:9]
	s_cbranch_execz .LBB0_665
	s_lshl_b32 s34, s66, 2
	v_lshlrev_b64 v[136:137], 6, v[136:137]
	s_ashr_i32 s35, s34, 31
	v_lshl_add_u64 v[136:137], s[18:19], 0, v[136:137]
	v_lshl_add_u64 v[136:137], s[34:35], 2, v[136:137]
	s_lshl_b32 s14, s42, 2
	s_waitcnt lgkmcnt(0)
	v_add_f32_e32 v1, v1, v138
	v_lshl_add_u64 v[136:137], v[136:137], 0, s[14:15]
	global_store_dword v[136:137], v1, off
.LBB0_665:
	s_or_b64 exec, exec, s[6:7]
	v_add_u32_e32 v136, 0xffff00b0, v210
	v_readlane_b32 s36, v254, 50
	v_ashrrev_i32_e32 v1, 5, v136
	v_readlane_b32 s37, v254, 51
	v_add_u32_e32 v1, 32, v1
	v_ashrrev_i32_e32 v137, 31, v136
	v_readlane_b32 s68, v254, 16
	s_waitcnt lgkmcnt(0)
	v_mov_b64_e32 v[138:139], s[36:37]
	v_lshlrev_b64 v[136:137], 12, v[136:137]
	v_readlane_b32 s70, v254, 18
	v_readlane_b32 s71, v254, 19
	v_mad_i64_i32 v[138:139], s[6:7], v1, s99, v[138:139]
	s_nop 0
	v_lshl_add_u64 v[136:137], s[70:71], 0, v[136:137]
	v_lshl_add_u64 v[152:153], v[138:139], 0, s[54:55]
	v_lshl_add_u64 v[154:155], v[136:137], 0, v[132:133]
	v_lshl_add_u64 v[132:133], v[152:153], 0, v[132:133]
	global_load_dwordx4 v[136:139], v[132:133], off
	global_load_dwordx4 v[140:143], v[154:155], off
	global_load_dwordx4 v[144:147], v[154:155], off offset:16
	global_load_dwordx4 v[148:151], v[132:133], off offset:16
	v_add_u32_e32 v132, 0xb0, v210
	v_ashrrev_i32_e32 v133, 31, v132
	v_lshlrev_b64 v[156:157], 11, v[132:133]
	v_lshl_add_u64 v[156:157], s[40:41], 0, v[156:157]
	v_lshl_add_u64 v[156:157], v[2:3], 1, v[156:157]
	v_lshl_add_u64 v[152:153], v[134:135], 2, v[152:153]
	v_readlane_b32 s69, v254, 17
	v_readlane_b32 s72, v254, 20
	v_readlane_b32 s73, v254, 21
	v_readlane_b32 s74, v254, 22
	v_readlane_b32 s75, v254, 23
	v_readlane_b32 s76, v254, 24
	v_readlane_b32 s77, v254, 25
	v_readlane_b32 s78, v254, 26
	v_readlane_b32 s79, v254, 27
	v_readlane_b32 s80, v254, 28
	v_readlane_b32 s81, v254, 29
	v_readlane_b32 s82, v254, 30
	v_readlane_b32 s83, v254, 31
	v_readlane_b32 s38, v254, 52
	v_readlane_b32 s39, v254, 53
	s_waitcnt vmcnt(2)
	v_pk_fma_f32 v[158:159], v[94:95], v[138:139], v[142:143]
	v_pk_fma_f32 v[160:161], v[92:93], v[136:137], v[140:141]
	s_waitcnt vmcnt(0)
	v_pk_fma_f32 v[150:151], v[98:99], v[150:151], v[146:147]
	v_pk_fma_f32 v[162:163], v[96:97], v[148:149], v[144:145]
	v_cvt_pk_bf16_f32 v134, v160, v161
	v_cvt_pk_bf16_f32 v135, v158, v159
	v_cvt_pk_bf16_f32 v136, v162, v163
	v_cvt_pk_bf16_f32 v137, v150, v151
	global_store_dwordx4 v[156:157], v[134:137], off sc1
	global_load_dwordx4 v[134:137], v[152:153], off
	s_nop 0
	global_load_dwordx4 v[138:141], v[154:155], off offset:512
	global_load_dwordx4 v[142:145], v[154:155], off offset:528
	global_load_dwordx4 v[146:149], v[152:153], off offset:16
	v_mul_f32_e32 v1, v161, v161
	v_mul_f32_e32 v152, v159, v159
	v_mul_f32_e32 v153, v163, v163
	v_fmac_f32_e32 v1, v160, v160
	v_fmac_f32_e32 v152, v158, v158
	v_mul_f32_e32 v151, v151, v151
	v_fmac_f32_e32 v153, v162, v162
	v_add_f32_e32 v1, v1, v152
	v_fmac_f32_e32 v151, v150, v150
	v_add_f32_e32 v1, v1, v153
	v_add_f32_e32 v1, v151, v1
	s_waitcnt vmcnt(2)
	v_pk_fma_f32 v[140:141], v[126:127], v[136:137], v[140:141]
	v_pk_fma_f32 v[134:135], v[124:125], v[134:135], v[138:139]
	s_waitcnt vmcnt(0)
	v_pk_fma_f32 v[138:139], v[128:129], v[146:147], v[142:143]
	v_mul_f32_e32 v136, v135, v135
	v_mul_f32_e32 v137, v141, v141
	v_pk_fma_f32 v[144:145], v[130:131], v[148:149], v[144:145]
	v_mul_f32_e32 v142, v139, v139
	v_fmac_f32_e32 v136, v134, v134
	v_fmac_f32_e32 v137, v140, v140
	v_mul_f32_e32 v143, v145, v145
	v_fmac_f32_e32 v142, v138, v138
	v_add_f32_e32 v136, v136, v137
	v_add_f32_e32 v136, v136, v142
	v_fmac_f32_e32 v143, v144, v144
	v_add_f32_e32 v136, v143, v136
	v_add_f32_e32 v1, v1, v136
	ds_bpermute_b32 v137, v226, v1
	v_cvt_pk_bf16_f32 v136, v134, v135
	v_cvt_pk_bf16_f32 v138, v138, v139
	v_cvt_pk_bf16_f32 v139, v144, v145
	s_waitcnt lgkmcnt(0)
	v_add_f32_e32 v1, v1, v137
	ds_bpermute_b32 v134, v227, v1
	v_cvt_pk_bf16_f32 v137, v140, v141
	global_store_dwordx4 v[156:157], v[136:139], off offset:256 sc1
	s_and_saveexec_b64 s[6:7], s[8:9]
	s_cbranch_execz .LBB0_667
	s_lshl_b32 s34, s66, 2
	v_lshlrev_b64 v[132:133], 6, v[132:133]
	s_ashr_i32 s35, s34, 31
	v_lshl_add_u64 v[132:133], s[18:19], 0, v[132:133]
	v_lshl_add_u64 v[132:133], s[34:35], 2, v[132:133]
	s_lshl_b32 s14, s42, 2
	s_waitcnt lgkmcnt(0)
	v_add_f32_e32 v1, v1, v134
	v_lshl_add_u64 v[132:133], v[132:133], 0, s[14:15]
	global_store_dword v[132:133], v1, off

.LBB0_668:
	s_and_b64 vcc, exec, s[6:7]
	s_cbranch_vccz .LBB0_686
	s_ashr_i32 s3, s90, 3
	s_mul_hi_i32 s7, s3, 0x3000
	s_mulk_i32 s3, 0x3000
	v_readlane_b32 s36, v254, 50
	v_readlane_b32 s37, v254, 51
	s_add_u32 s6, s36, s3
	s_addc_u32 s7, s37, s7
	v_lshlrev_b64 v[132:133], 2, v[2:3]
	v_readlane_b32 s68, v254, 16
	s_waitcnt lgkmcnt(0)
	v_lshl_add_u64 v[134:135], s[6:7], 0, v[132:133]
	v_readlane_b32 s69, v254, 17
	v_lshl_add_u64 v[148:149], v[134:135], 0, s[54:55]
	v_add_co_u32_e32 v134, vcc, 0x2000, v134
	v_lshl_add_u64 v[212:213], s[68:69], 0, v[132:133]
	v_lshlrev_b64 v[132:133], 12, v[210:211]
	v_addc_co_u32_e32 v135, vcc, 0, v135, vcc
	v_lshl_add_u64 v[132:133], v[212:213], 0, v[132:133]
	global_load_dwordx4 v[232:235], v[132:133], off offset:16 nt
	global_load_dwordx4 v[140:143], v[148:149], off offset:16
	global_load_dwordx4 v[136:139], v[148:149], off offset:512
	global_load_dwordx4 v[236:239], v[132:133], off offset:512 nt
	global_load_dwordx4 v[144:147], v[134:135], off
	global_load_dwordx4 v[240:243], v[132:133], off nt
	global_load_dwordx4 v[244:247], v[132:133], off offset:528 nt
	s_nop 0
	global_load_dwordx4 v[132:135], v[148:149], off offset:528
	v_or_b32_e32 v218, 16, v210
	v_or_b32_e32 v216, 32, v210
	v_or_b32_e32 v214, 48, v210
	v_ashrrev_i32_e32 v219, 31, v218
	v_ashrrev_i32_e32 v217, 31, v216
	v_ashrrev_i32_e32 v215, 31, v214
	v_lshlrev_b64 v[148:149], 12, v[218:219]
	v_lshlrev_b64 v[150:151], 12, v[216:217]
	v_lshlrev_b64 v[152:153], 12, v[214:215]
	v_lshl_add_u64 v[148:149], v[212:213], 0, v[148:149]
	v_lshl_add_u64 v[150:151], v[212:213], 0, v[150:151]
	v_lshl_add_u64 v[152:153], v[212:213], 0, v[152:153]
	global_load_dwordx4 v[188:191], v[148:149], off offset:16 nt
	global_load_dwordx4 v[192:195], v[148:149], off nt
	global_load_dwordx4 v[180:183], v[148:149], off offset:528 nt
	global_load_dwordx4 v[184:187], v[148:149], off offset:512 nt
	global_load_dwordx4 v[172:175], v[150:151], off offset:16 nt
	global_load_dwordx4 v[176:179], v[150:151], off nt
	global_load_dwordx4 v[164:167], v[150:151], off offset:528 nt
	global_load_dwordx4 v[168:171], v[150:151], off offset:512 nt
	global_load_dwordx4 v[156:159], v[152:153], off offset:16 nt
	global_load_dwordx4 v[160:163], v[152:153], off nt
	s_nop 0
	global_load_dwordx4 v[148:151], v[152:153], off offset:528 nt
	s_nop 0
	global_load_dwordx4 v[152:155], v[152:153], off offset:512 nt
	v_readlane_b32 s38, v254, 52
	v_readlane_b32 s39, v254, 53
	v_readlane_b32 s70, v254, 18
	v_readlane_b32 s71, v254, 19
	v_readlane_b32 s72, v254, 20
	v_readlane_b32 s73, v254, 21
	v_readlane_b32 s74, v254, 22
	v_readlane_b32 s75, v254, 23
	v_readlane_b32 s76, v254, 24
	v_readlane_b32 s77, v254, 25
	v_readlane_b32 s78, v254, 26
	v_readlane_b32 s79, v254, 27
	v_readlane_b32 s80, v254, 28
	v_readlane_b32 s81, v254, 29
	v_readlane_b32 s82, v254, 30
	v_readlane_b32 s83, v254, 31
	s_waitcnt vmcnt(0)
	v_pk_fma_f32 v[248:249], v[10:11], v[142:143], v[234:235]
	v_pk_fma_f32 v[232:233], v[8:9], v[140:141], v[232:233]
	v_mul_f32_e32 v231, v249, v249
	v_cvt_pk_bf16_f32 v235, v248, v249
	v_pk_fma_f32 v[242:243], v[6:7], v[146:147], v[242:243]
	v_pk_fma_f32 v[240:241], v[4:5], v[144:145], v[240:241]
	v_mul_f32_e32 v252, v243, v243
	v_mul_f32_e32 v249, v241, v241
	v_mul_f32_e32 v1, v233, v233
	v_fmac_f32_e32 v249, v240, v240
	v_fmac_f32_e32 v252, v242, v242
	v_pk_fma_f32 v[236:237], v[36:37], v[136:137], v[236:237]
	v_cvt_pk_bf16_f32 v234, v232, v233
	v_fmac_f32_e32 v1, v232, v232
	v_cvt_pk_bf16_f32 v232, v240, v241
	v_add_f32_e32 v240, v249, v252
	v_pk_fma_f32 v[238:239], v[38:39], v[138:139], v[238:239]
	v_mul_f32_e32 v250, v237, v237
	v_fmac_f32_e32 v231, v248, v248
	v_add_f32_e32 v1, v240, v1
	v_pk_fma_f32 v[244:245], v[40:41], v[132:133], v[244:245]
	v_mul_f32_e32 v251, v239, v239
	v_fmac_f32_e32 v250, v236, v236
	v_add_f32_e32 v1, v231, v1
	v_pk_fma_f32 v[246:247], v[42:43], v[134:135], v[246:247]
	v_fmac_f32_e32 v251, v238, v238
	v_mul_f32_e32 v248, v245, v245
	v_add_f32_e32 v1, v250, v1
	v_mul_f32_e32 v253, v247, v247
	v_fmac_f32_e32 v248, v244, v244
	v_add_f32_e32 v1, v251, v1
	v_fmac_f32_e32 v253, v246, v246
	v_add_f32_e32 v1, v248, v1
	v_add_f32_e32 v1, v253, v1
	ds_bpermute_b32 v231, v226, v1
	v_lshlrev_b64 v[240:241], 11, v[210:211]
	v_lshl_add_u64 v[240:241], s[40:41], 0, v[240:241]
	v_cvt_pk_bf16_f32 v233, v242, v243
	v_lshl_add_u64 v[240:241], v[2:3], 1, v[240:241]
	s_waitcnt lgkmcnt(0)
	v_add_f32_e32 v1, v1, v231
	ds_bpermute_b32 v231, v227, v1
	global_store_dwordx4 v[240:241], v[232:235], off sc1
	s_nop 1
	v_cvt_pk_bf16_f32 v232, v236, v237
	v_cvt_pk_bf16_f32 v233, v238, v239
	v_cvt_pk_bf16_f32 v234, v244, v245
	v_cvt_pk_bf16_f32 v235, v246, v247
	global_store_dwordx4 v[240:241], v[232:235], off offset:256 sc1
	s_and_saveexec_b64 s[6:7], s[8:9]
	s_cbranch_execz .LBB0_671
	s_lshl_b32 s34, s66, 2
	v_lshlrev_b64 v[232:233], 6, v[210:211]
	s_ashr_i32 s35, s34, 31
	v_lshl_add_u64 v[232:233], s[18:19], 0, v[232:233]
	v_lshl_add_u64 v[232:233], s[34:35], 2, v[232:233]
	s_lshl_b32 s14, s42, 2
	s_waitcnt lgkmcnt(0)
	v_add_f32_e32 v1, v1, v231
	v_lshl_add_u64 v[232:233], v[232:233], 0, s[14:15]
	global_store_dword v[232:233], v1, off
.LBB0_671:
	s_or_b64 exec, exec, s[6:7]
	v_pk_fma_f32 v[194:195], v[14:15], v[146:147], v[194:195]
	v_pk_fma_f32 v[192:193], v[12:13], v[144:145], v[192:193]
	v_pk_fma_f32 v[234:235], v[48:49], v[132:133], v[180:181]
	v_mul_f32_e32 v1, v193, v193
	v_mul_f32_e32 v180, v195, v195
	v_pk_fma_f32 v[188:189], v[16:17], v[140:141], v[188:189]
	v_fmac_f32_e32 v1, v192, v192
	v_fmac_f32_e32 v180, v194, v194
	v_add_f32_e32 v1, v1, v180
	v_mul_f32_e32 v180, v189, v189
	v_pk_fma_f32 v[190:191], v[18:19], v[142:143], v[190:191]
	v_fmac_f32_e32 v180, v188, v188
	v_add_f32_e32 v1, v1, v180
	v_mul_f32_e32 v180, v191, v191
	v_pk_fma_f32 v[184:185], v[44:45], v[136:137], v[184:185]
	v_fmac_f32_e32 v180, v190, v190
	v_add_f32_e32 v1, v180, v1
	v_mul_f32_e32 v180, v185, v185
	v_pk_fma_f32 v[186:187], v[46:47], v[138:139], v[186:187]
	v_fmac_f32_e32 v180, v184, v184
	v_add_f32_e32 v1, v180, v1
	v_mul_f32_e32 v180, v187, v187
	v_fmac_f32_e32 v180, v186, v186
	v_add_f32_e32 v1, v180, v1
	v_mul_f32_e32 v180, v235, v235
	v_pk_fma_f32 v[232:233], v[50:51], v[134:135], v[182:183]
	v_fmac_f32_e32 v180, v234, v234
	v_add_f32_e32 v1, v180, v1
	v_mul_f32_e32 v180, v233, v233
	v_fmac_f32_e32 v180, v232, v232
	v_add_f32_e32 v1, v180, v1
	v_cvt_pk_bf16_f32 v183, v190, v191
	ds_bpermute_b32 v190, v226, v1
	v_cvt_pk_bf16_f32 v182, v188, v189
	v_lshlrev_b64 v[188:189], 11, v[218:219]
	v_lshl_add_u64 v[188:189], s[40:41], 0, v[188:189]
	v_cvt_pk_bf16_f32 v180, v192, v193
	v_cvt_pk_bf16_f32 v181, v194, v195
	v_lshl_add_u64 v[188:189], v[2:3], 1, v[188:189]
	s_waitcnt lgkmcnt(0)
	v_add_f32_e32 v1, v1, v190
	global_store_dwordx4 v[188:189], v[180:183], off sc1
	ds_bpermute_b32 v180, v227, v1
	s_nop 0
	v_cvt_pk_bf16_f32 v182, v184, v185
	v_cvt_pk_bf16_f32 v183, v186, v187
	v_cvt_pk_bf16_f32 v184, v234, v235
	v_cvt_pk_bf16_f32 v185, v232, v233
	global_store_dwordx4 v[188:189], v[182:185], off offset:256 sc1
	s_and_saveexec_b64 s[6:7], s[8:9]
	s_cbranch_execz .LBB0_673
	s_waitcnt lgkmcnt(0)
	v_add_f32_e32 v1, v1, v180
	s_lshl_b32 s34, s66, 2
	v_lshlrev_b64 v[180:181], 6, v[218:219]
	s_ashr_i32 s35, s34, 31
	v_lshl_add_u64 v[180:181], s[18:19], 0, v[180:181]
	v_lshl_add_u64 v[180:181], s[34:35], 2, v[180:181]
	s_lshl_b32 s14, s42, 2
	v_lshl_add_u64 v[180:181], v[180:181], 0, s[14:15]
	global_store_dword v[180:181], v1, off
.LBB0_673:
	s_or_b64 exec, exec, s[6:7]
	v_pk_fma_f32 v[178:179], v[22:23], v[146:147], v[178:179]
	v_pk_fma_f32 v[176:177], v[20:21], v[144:145], v[176:177]
	v_pk_fma_f32 v[182:183], v[56:57], v[132:133], v[164:165]
	v_mul_f32_e32 v1, v177, v177
	v_mul_f32_e32 v164, v179, v179
	v_pk_fma_f32 v[172:173], v[24:25], v[140:141], v[172:173]
	v_fmac_f32_e32 v1, v176, v176
	v_fmac_f32_e32 v164, v178, v178
	v_add_f32_e32 v1, v1, v164
	v_mul_f32_e32 v164, v173, v173
	v_pk_fma_f32 v[174:175], v[26:27], v[142:143], v[174:175]
	v_fmac_f32_e32 v164, v172, v172
	v_add_f32_e32 v1, v1, v164
	v_mul_f32_e32 v164, v175, v175
	v_pk_fma_f32 v[168:169], v[52:53], v[136:137], v[168:169]
	v_fmac_f32_e32 v164, v174, v174
	v_add_f32_e32 v1, v164, v1
	v_mul_f32_e32 v164, v169, v169
	v_pk_fma_f32 v[170:171], v[54:55], v[138:139], v[170:171]
	v_fmac_f32_e32 v164, v168, v168
	v_add_f32_e32 v1, v164, v1
	v_mul_f32_e32 v164, v171, v171
	v_fmac_f32_e32 v164, v170, v170
	v_add_f32_e32 v1, v164, v1
	v_mul_f32_e32 v164, v183, v183
	s_waitcnt lgkmcnt(0)
	v_pk_fma_f32 v[180:181], v[58:59], v[134:135], v[166:167]
	v_fmac_f32_e32 v164, v182, v182
	v_add_f32_e32 v1, v164, v1
	v_mul_f32_e32 v164, v181, v181
	v_fmac_f32_e32 v164, v180, v180
	v_add_f32_e32 v1, v164, v1
	v_cvt_pk_bf16_f32 v167, v174, v175
	ds_bpermute_b32 v174, v226, v1
	v_cvt_pk_bf16_f32 v166, v172, v173
	v_lshlrev_b64 v[172:173], 11, v[216:217]
	v_lshl_add_u64 v[172:173], s[40:41], 0, v[172:173]
	v_cvt_pk_bf16_f32 v164, v176, v177
	v_cvt_pk_bf16_f32 v165, v178, v179
	v_lshl_add_u64 v[172:173], v[2:3], 1, v[172:173]
	s_waitcnt lgkmcnt(0)
	v_add_f32_e32 v1, v1, v174
	global_store_dwordx4 v[172:173], v[164:167], off sc1
	ds_bpermute_b32 v164, v227, v1
	s_nop 0
	v_cvt_pk_bf16_f32 v166, v168, v169
	v_cvt_pk_bf16_f32 v167, v170, v171
	v_cvt_pk_bf16_f32 v168, v182, v183
	v_cvt_pk_bf16_f32 v169, v180, v181
	global_store_dwordx4 v[172:173], v[166:169], off offset:256 sc1
	s_and_saveexec_b64 s[6:7], s[8:9]
	s_cbranch_execz .LBB0_675
	s_waitcnt lgkmcnt(0)
	v_add_f32_e32 v1, v1, v164
	s_lshl_b32 s34, s66, 2
	v_lshlrev_b64 v[164:165], 6, v[216:217]
	s_ashr_i32 s35, s34, 31
	v_lshl_add_u64 v[164:165], s[18:19], 0, v[164:165]
	v_lshl_add_u64 v[164:165], s[34:35], 2, v[164:165]
	s_lshl_b32 s14, s42, 2
	v_lshl_add_u64 v[164:165], v[164:165], 0, s[14:15]
	global_store_dword v[164:165], v1, off
.LBB0_675:
	s_or_b64 exec, exec, s[6:7]
	v_pk_fma_f32 v[162:163], v[30:31], v[146:147], v[162:163]
	v_pk_fma_f32 v[160:161], v[28:29], v[144:145], v[160:161]
	v_pk_fma_f32 v[166:167], v[64:65], v[132:133], v[148:149]
	v_mul_f32_e32 v1, v161, v161
	v_mul_f32_e32 v148, v163, v163
	v_pk_fma_f32 v[156:157], v[32:33], v[140:141], v[156:157]
	v_fmac_f32_e32 v1, v160, v160
	v_fmac_f32_e32 v148, v162, v162
	v_add_f32_e32 v1, v1, v148
	v_mul_f32_e32 v148, v157, v157
	v_pk_fma_f32 v[158:159], v[34:35], v[142:143], v[158:159]
	v_fmac_f32_e32 v148, v156, v156
	v_add_f32_e32 v1, v1, v148
	v_mul_f32_e32 v148, v159, v159
	v_pk_fma_f32 v[152:153], v[60:61], v[136:137], v[152:153]
	v_fmac_f32_e32 v148, v158, v158
	v_add_f32_e32 v1, v148, v1
	v_mul_f32_e32 v148, v153, v153
	v_pk_fma_f32 v[154:155], v[62:63], v[138:139], v[154:155]
	v_fmac_f32_e32 v148, v152, v152
	v_add_f32_e32 v1, v148, v1
	v_mul_f32_e32 v148, v155, v155
	v_fmac_f32_e32 v148, v154, v154
	v_add_f32_e32 v1, v148, v1
	v_mul_f32_e32 v148, v167, v167
	s_waitcnt lgkmcnt(0)
	v_pk_fma_f32 v[164:165], v[66:67], v[134:135], v[150:151]
	v_fmac_f32_e32 v148, v166, v166
	v_add_f32_e32 v1, v148, v1
	v_mul_f32_e32 v148, v165, v165
	v_fmac_f32_e32 v148, v164, v164
	v_add_f32_e32 v1, v148, v1
	v_cvt_pk_bf16_f32 v151, v158, v159
	ds_bpermute_b32 v158, v226, v1
	v_cvt_pk_bf16_f32 v150, v156, v157
	v_lshlrev_b64 v[156:157], 11, v[214:215]
	v_lshl_add_u64 v[156:157], s[40:41], 0, v[156:157]
	v_cvt_pk_bf16_f32 v148, v160, v161
	v_cvt_pk_bf16_f32 v149, v162, v163
	v_lshl_add_u64 v[156:157], v[2:3], 1, v[156:157]
	s_waitcnt lgkmcnt(0)
	v_add_f32_e32 v1, v1, v158
	global_store_dwordx4 v[156:157], v[148:151], off sc1
	ds_bpermute_b32 v148, v227, v1
	s_nop 0
	v_cvt_pk_bf16_f32 v150, v152, v153
	v_cvt_pk_bf16_f32 v151, v154, v155
	v_cvt_pk_bf16_f32 v152, v166, v167
	v_cvt_pk_bf16_f32 v153, v164, v165
	global_store_dwordx4 v[156:157], v[150:153], off offset:256 sc1
	s_and_saveexec_b64 s[6:7], s[8:9]
	s_cbranch_execz .LBB0_677
	s_waitcnt lgkmcnt(0)
	v_add_f32_e32 v1, v1, v148
	s_lshl_b32 s34, s66, 2
	v_lshlrev_b64 v[148:149], 6, v[214:215]
	s_ashr_i32 s35, s34, 31
	v_lshl_add_u64 v[148:149], s[18:19], 0, v[148:149]
	v_lshl_add_u64 v[148:149], s[34:35], 2, v[148:149]
	s_lshl_b32 s14, s42, 2
	v_lshl_add_u64 v[148:149], v[148:149], 0, s[14:15]
	global_store_dword v[148:149], v1, off
.LBB0_677:
	s_or_b64 exec, exec, s[6:7]
	v_add_u32_e32 v218, 0x80, v210
	v_ashrrev_i32_e32 v219, 31, v218
	s_waitcnt lgkmcnt(0)
	v_lshlrev_b64 v[148:149], 12, v[218:219]
	v_lshl_add_u64 v[148:149], v[212:213], 0, v[148:149]
	global_load_dwordx4 v[232:235], v[148:149], off nt
	global_load_dwordx4 v[236:239], v[148:149], off offset:16 nt
	global_load_dwordx4 v[240:243], v[148:149], off offset:512 nt
	global_load_dwordx4 v[244:247], v[148:149], off offset:528 nt
	v_add_u32_e32 v216, 0x90, v210
	v_add_u32_e32 v214, 0xa0, v210
	v_add_u32_e32 v210, 0xb0, v210
	v_ashrrev_i32_e32 v217, 31, v216
	v_ashrrev_i32_e32 v215, 31, v214
	v_ashrrev_i32_e32 v211, 31, v210
	v_lshlrev_b64 v[148:149], 12, v[216:217]
	v_lshlrev_b64 v[150:151], 12, v[214:215]
	v_lshlrev_b64 v[152:153], 12, v[210:211]
	v_lshl_add_u64 v[148:149], v[212:213], 0, v[148:149]
	v_lshl_add_u64 v[150:151], v[212:213], 0, v[150:151]
	v_lshl_add_u64 v[152:153], v[212:213], 0, v[152:153]
	global_load_dwordx4 v[188:191], v[148:149], off offset:16 nt
	global_load_dwordx4 v[192:195], v[148:149], off nt
	global_load_dwordx4 v[180:183], v[148:149], off offset:528 nt
	global_load_dwordx4 v[184:187], v[148:149], off offset:512 nt
	global_load_dwordx4 v[172:175], v[150:151], off offset:16 nt
	global_load_dwordx4 v[176:179], v[150:151], off nt
	global_load_dwordx4 v[164:167], v[150:151], off offset:528 nt
	global_load_dwordx4 v[168:171], v[150:151], off offset:512 nt
	global_load_dwordx4 v[156:159], v[152:153], off offset:16 nt
	global_load_dwordx4 v[160:163], v[152:153], off nt
	s_nop 0
	global_load_dwordx4 v[148:151], v[152:153], off offset:528 nt
	s_nop 0
	global_load_dwordx4 v[152:155], v[152:153], off offset:512 nt
	s_waitcnt vmcnt(15)
	v_pk_fma_f32 v[212:213], v[70:71], v[146:147], v[234:235]
	v_pk_fma_f32 v[248:249], v[68:69], v[144:145], v[232:233]
	s_waitcnt vmcnt(14)
	v_pk_fma_f32 v[236:237], v[72:73], v[140:141], v[236:237]
	v_mul_f32_e32 v1, v249, v249
	v_mul_f32_e32 v231, v213, v213
	v_pk_fma_f32 v[238:239], v[74:75], v[142:143], v[238:239]
	v_mul_f32_e32 v250, v237, v237
	v_fmac_f32_e32 v1, v248, v248
	v_fmac_f32_e32 v231, v212, v212
	s_waitcnt vmcnt(13)
	v_pk_fma_f32 v[240:241], v[100:101], v[136:137], v[240:241]
	v_mul_f32_e32 v251, v239, v239
	v_fmac_f32_e32 v250, v236, v236
	v_add_f32_e32 v1, v1, v231
	v_pk_fma_f32 v[242:243], v[102:103], v[138:139], v[242:243]
	v_mul_f32_e32 v252, v241, v241
	v_fmac_f32_e32 v251, v238, v238
	v_add_f32_e32 v1, v1, v250
	s_waitcnt vmcnt(12)
	v_pk_fma_f32 v[244:245], v[104:105], v[132:133], v[244:245]
	v_mul_f32_e32 v253, v243, v243
	v_fmac_f32_e32 v252, v240, v240
	v_add_f32_e32 v1, v251, v1
	v_pk_fma_f32 v[246:247], v[106:107], v[134:135], v[246:247]
	v_mul_f32_e32 v222, v245, v245
	v_fmac_f32_e32 v253, v242, v242
	v_add_f32_e32 v1, v252, v1
	v_mul_f32_e32 v196, v247, v247
	v_fmac_f32_e32 v222, v244, v244
	v_add_f32_e32 v1, v253, v1
	v_fmac_f32_e32 v196, v246, v246
	v_add_f32_e32 v1, v222, v1
	v_add_f32_e32 v1, v196, v1
	ds_bpermute_b32 v196, v226, v1
	v_cvt_pk_bf16_f32 v233, v212, v213
	v_lshlrev_b64 v[212:213], 11, v[218:219]
	v_lshl_add_u64 v[212:213], s[40:41], 0, v[212:213]
	v_cvt_pk_bf16_f32 v234, v236, v237
	s_waitcnt lgkmcnt(0)
	v_add_f32_e32 v1, v1, v196
	v_lshl_add_u64 v[236:237], v[2:3], 1, v[212:213]
	ds_bpermute_b32 v212, v227, v1
	v_cvt_pk_bf16_f32 v232, v248, v249
	v_cvt_pk_bf16_f32 v235, v238, v239
	global_store_dwordx4 v[236:237], v[232:235], off sc1
	s_nop 1
	v_cvt_pk_bf16_f32 v232, v240, v241
	v_cvt_pk_bf16_f32 v233, v242, v243
	v_cvt_pk_bf16_f32 v234, v244, v245
	v_cvt_pk_bf16_f32 v235, v246, v247
	global_store_dwordx4 v[236:237], v[232:235], off offset:256 sc1
	s_and_saveexec_b64 s[6:7], s[8:9]
	s_cbranch_execz .LBB0_679
	s_waitcnt lgkmcnt(0)
	v_add_f32_e32 v1, v1, v212
	s_lshl_b32 s34, s66, 2
	v_lshlrev_b64 v[212:213], 6, v[218:219]
	s_ashr_i32 s35, s34, 31
	v_lshl_add_u64 v[212:213], s[18:19], 0, v[212:213]
	v_lshl_add_u64 v[212:213], s[34:35], 2, v[212:213]
	s_lshl_b32 s14, s42, 2
	v_lshl_add_u64 v[212:213], v[212:213], 0, s[14:15]
	global_store_dword v[212:213], v1, off
.LBB0_679:
	s_or_b64 exec, exec, s[6:7]
	s_waitcnt vmcnt(12)
	v_pk_fma_f32 v[194:195], v[78:79], v[146:147], v[194:195]
	v_pk_fma_f32 v[192:193], v[76:77], v[144:145], v[192:193]
	s_waitcnt vmcnt(11)
	v_pk_fma_f32 v[218:219], v[112:113], v[132:133], v[180:181]
	v_mul_f32_e32 v1, v193, v193
	v_mul_f32_e32 v180, v195, v195
	v_pk_fma_f32 v[188:189], v[80:81], v[140:141], v[188:189]
	v_fmac_f32_e32 v1, v192, v192
	v_fmac_f32_e32 v180, v194, v194
	v_add_f32_e32 v1, v1, v180
	v_mul_f32_e32 v180, v189, v189
	v_pk_fma_f32 v[190:191], v[82:83], v[142:143], v[190:191]
	v_fmac_f32_e32 v180, v188, v188
	v_add_f32_e32 v1, v1, v180
	v_mul_f32_e32 v180, v191, v191
	s_waitcnt vmcnt(10)
	v_pk_fma_f32 v[184:185], v[108:109], v[136:137], v[184:185]
	v_fmac_f32_e32 v180, v190, v190
	v_add_f32_e32 v1, v180, v1
	v_mul_f32_e32 v180, v185, v185
	v_pk_fma_f32 v[186:187], v[110:111], v[138:139], v[186:187]
	v_fmac_f32_e32 v180, v184, v184
	v_add_f32_e32 v1, v180, v1
	v_mul_f32_e32 v180, v187, v187
	v_fmac_f32_e32 v180, v186, v186
	v_add_f32_e32 v1, v180, v1
	v_mul_f32_e32 v180, v219, v219
	s_waitcnt lgkmcnt(0)
	v_pk_fma_f32 v[212:213], v[114:115], v[134:135], v[182:183]
	v_fmac_f32_e32 v180, v218, v218
	v_add_f32_e32 v1, v180, v1
	v_mul_f32_e32 v180, v213, v213
	v_fmac_f32_e32 v180, v212, v212
	v_add_f32_e32 v1, v180, v1
	v_cvt_pk_bf16_f32 v183, v190, v191
	ds_bpermute_b32 v190, v226, v1
	v_cvt_pk_bf16_f32 v182, v188, v189
	v_lshlrev_b64 v[188:189], 11, v[216:217]
	v_lshl_add_u64 v[188:189], s[40:41], 0, v[188:189]
	v_cvt_pk_bf16_f32 v180, v192, v193
	v_cvt_pk_bf16_f32 v181, v194, v195
	v_lshl_add_u64 v[188:189], v[2:3], 1, v[188:189]
	s_waitcnt lgkmcnt(0)
	v_add_f32_e32 v1, v1, v190
	global_store_dwordx4 v[188:189], v[180:183], off sc1
	ds_bpermute_b32 v180, v227, v1
	s_nop 0
	v_cvt_pk_bf16_f32 v182, v184, v185
	v_cvt_pk_bf16_f32 v183, v186, v187
	v_cvt_pk_bf16_f32 v184, v218, v219
	v_cvt_pk_bf16_f32 v185, v212, v213
	global_store_dwordx4 v[188:189], v[182:185], off offset:256 sc1
	s_and_saveexec_b64 s[6:7], s[8:9]
	s_cbranch_execz .LBB0_681
	s_waitcnt lgkmcnt(0)
	v_add_f32_e32 v1, v1, v180
	s_lshl_b32 s34, s66, 2
	v_lshlrev_b64 v[180:181], 6, v[216:217]
	s_ashr_i32 s35, s34, 31
	v_lshl_add_u64 v[180:181], s[18:19], 0, v[180:181]
	v_lshl_add_u64 v[180:181], s[34:35], 2, v[180:181]
	s_lshl_b32 s14, s42, 2
	v_lshl_add_u64 v[180:181], v[180:181], 0, s[14:15]
	global_store_dword v[180:181], v1, off
.LBB0_681:
	s_or_b64 exec, exec, s[6:7]
	s_waitcnt vmcnt(10)
	v_pk_fma_f32 v[178:179], v[86:87], v[146:147], v[178:179]
	v_pk_fma_f32 v[176:177], v[84:85], v[144:145], v[176:177]
	s_waitcnt vmcnt(9)
	v_pk_fma_f32 v[182:183], v[120:121], v[132:133], v[164:165]
	v_mul_f32_e32 v1, v177, v177
	v_mul_f32_e32 v164, v179, v179
	v_pk_fma_f32 v[172:173], v[88:89], v[140:141], v[172:173]
	v_fmac_f32_e32 v1, v176, v176
	v_fmac_f32_e32 v164, v178, v178
	v_add_f32_e32 v1, v1, v164
	v_mul_f32_e32 v164, v173, v173
	v_pk_fma_f32 v[174:175], v[90:91], v[142:143], v[174:175]
	v_fmac_f32_e32 v164, v172, v172
	v_add_f32_e32 v1, v1, v164
	v_mul_f32_e32 v164, v175, v175
	s_waitcnt vmcnt(8)
	v_pk_fma_f32 v[168:169], v[116:117], v[136:137], v[168:169]
	v_fmac_f32_e32 v164, v174, v174
	v_add_f32_e32 v1, v164, v1
	v_mul_f32_e32 v164, v169, v169
	v_pk_fma_f32 v[170:171], v[118:119], v[138:139], v[170:171]
	v_fmac_f32_e32 v164, v168, v168
	v_add_f32_e32 v1, v164, v1
	v_mul_f32_e32 v164, v171, v171
	v_fmac_f32_e32 v164, v170, v170
	v_add_f32_e32 v1, v164, v1
	v_mul_f32_e32 v164, v183, v183
	s_waitcnt lgkmcnt(0)
	v_pk_fma_f32 v[180:181], v[122:123], v[134:135], v[166:167]
	v_fmac_f32_e32 v164, v182, v182
	v_add_f32_e32 v1, v164, v1
	v_mul_f32_e32 v164, v181, v181
	v_fmac_f32_e32 v164, v180, v180
	v_add_f32_e32 v1, v164, v1
	v_cvt_pk_bf16_f32 v167, v174, v175
	ds_bpermute_b32 v174, v226, v1
	v_cvt_pk_bf16_f32 v166, v172, v173
	v_lshlrev_b64 v[172:173], 11, v[214:215]
	v_lshl_add_u64 v[172:173], s[40:41], 0, v[172:173]
	v_cvt_pk_bf16_f32 v164, v176, v177
	v_cvt_pk_bf16_f32 v165, v178, v179
	v_lshl_add_u64 v[172:173], v[2:3], 1, v[172:173]
	s_waitcnt lgkmcnt(0)
	v_add_f32_e32 v1, v1, v174
	global_store_dwordx4 v[172:173], v[164:167], off sc1
	ds_bpermute_b32 v164, v227, v1
	s_nop 0
	v_cvt_pk_bf16_f32 v166, v168, v169
	v_cvt_pk_bf16_f32 v167, v170, v171
	v_cvt_pk_bf16_f32 v168, v182, v183
	v_cvt_pk_bf16_f32 v169, v180, v181
	global_store_dwordx4 v[172:173], v[166:169], off offset:256 sc1
	s_and_saveexec_b64 s[6:7], s[8:9]
	s_cbranch_execz .LBB0_683
	s_waitcnt lgkmcnt(0)
	v_add_f32_e32 v1, v1, v164
	s_lshl_b32 s34, s66, 2
	v_lshlrev_b64 v[164:165], 6, v[214:215]
	s_ashr_i32 s35, s34, 31
	v_lshl_add_u64 v[164:165], s[18:19], 0, v[164:165]
	v_lshl_add_u64 v[164:165], s[34:35], 2, v[164:165]
	s_lshl_b32 s14, s42, 2
	v_lshl_add_u64 v[164:165], v[164:165], 0, s[14:15]
	global_store_dword v[164:165], v1, off
.LBB0_683:
	s_or_b64 exec, exec, s[6:7]
	s_waitcnt vmcnt(8)
	v_pk_fma_f32 v[146:147], v[94:95], v[146:147], v[162:163]
	v_pk_fma_f32 v[144:145], v[92:93], v[144:145], v[160:161]
	s_waitcnt vmcnt(7)
	v_pk_fma_f32 v[148:149], v[128:129], v[132:133], v[148:149]
	v_mul_f32_e32 v1, v145, v145
	v_mul_f32_e32 v132, v147, v147
	v_pk_fma_f32 v[140:141], v[96:97], v[140:141], v[156:157]
	v_fmac_f32_e32 v1, v144, v144
	v_fmac_f32_e32 v132, v146, v146
	v_add_f32_e32 v1, v1, v132
	v_mul_f32_e32 v132, v141, v141
	v_pk_fma_f32 v[142:143], v[98:99], v[142:143], v[158:159]
	v_fmac_f32_e32 v132, v140, v140
	v_add_f32_e32 v1, v1, v132
	v_mul_f32_e32 v132, v143, v143
	s_waitcnt vmcnt(6)
	v_pk_fma_f32 v[136:137], v[124:125], v[136:137], v[152:153]
	v_fmac_f32_e32 v132, v142, v142
	v_add_f32_e32 v1, v132, v1
	v_mul_f32_e32 v132, v137, v137
	v_pk_fma_f32 v[138:139], v[126:127], v[138:139], v[154:155]
	v_fmac_f32_e32 v132, v136, v136
	v_add_f32_e32 v1, v132, v1
	v_mul_f32_e32 v132, v139, v139
	v_fmac_f32_e32 v132, v138, v138
	v_add_f32_e32 v1, v132, v1
	v_mul_f32_e32 v132, v149, v149
	v_pk_fma_f32 v[150:151], v[130:131], v[134:135], v[150:151]
	v_fmac_f32_e32 v132, v148, v148
	v_add_f32_e32 v1, v132, v1
	v_mul_f32_e32 v132, v151, v151
	v_fmac_f32_e32 v132, v150, v150
	v_add_f32_e32 v1, v132, v1
	v_cvt_pk_bf16_f32 v135, v142, v143
	ds_bpermute_b32 v142, v226, v1
	v_cvt_pk_bf16_f32 v134, v140, v141
	v_lshlrev_b64 v[140:141], 11, v[210:211]
	v_lshl_add_u64 v[140:141], s[40:41], 0, v[140:141]
	v_lshl_add_u64 v[140:141], v[2:3], 1, v[140:141]
	s_waitcnt lgkmcnt(0)
	v_add_f32_e32 v1, v1, v142
	ds_bpermute_b32 v2, v227, v1
	v_cvt_pk_bf16_f32 v132, v144, v145
	v_cvt_pk_bf16_f32 v133, v146, v147
	global_store_dwordx4 v[140:141], v[132:135], off sc1
	s_nop 1
	v_cvt_pk_bf16_f32 v132, v136, v137
	v_cvt_pk_bf16_f32 v133, v138, v139
	v_cvt_pk_bf16_f32 v134, v148, v149
	v_cvt_pk_bf16_f32 v135, v150, v151
	global_store_dwordx4 v[140:141], v[132:135], off offset:256 sc1
	s_and_saveexec_b64 s[6:7], s[8:9]
	s_cbranch_execz .LBB0_685
	s_waitcnt lgkmcnt(0)
	v_add_f32_e32 v1, v1, v2
	s_lshl_b32 s34, s66, 2
	v_lshlrev_b64 v[2:3], 6, v[210:211]
	s_ashr_i32 s35, s34, 31
	v_lshl_add_u64 v[2:3], s[18:19], 0, v[2:3]
	v_lshl_add_u64 v[2:3], s[34:35], 2, v[2:3]
	s_lshl_b32 s14, s42, 2
	v_lshl_add_u64 v[2:3], v[2:3], 0, s[14:15]
	global_store_dword v[2:3], v1, off
